# M2: placement: third K-loop MFMA run at 0 mod 8, load phase 4 body kept at its previous byte phase
# baseline (speedup 1.0000x reference)
; #define PG8_STAGE(bufoff, gbase, voff) do { _Pragma("unroll") for (int _i = 0; _i < 2; ++_i) { unsigned _vo = (voff)[_i]; asm volatile("" : "+v"(_vo));   \
;         __builtin_amdgcn_global_load_lds((const unsigned*)((const char*)(gbase) + _vo), (LAS unsigned*)(lds + (bufoff) + ldsw + _i * 8192), 16, 0, 0); } } while (0)
; #define PG8_LDA(dst, b, h) do { _Pragma("unroll") for (int m = 0; m < 4; ++m) _Pragma("unroll") for (int k = 0; k < 2; ++k) dst[m][k] = *(const LAS bf16x8*)(lds + PG8_SA(b, h) + aoff + m * 2048 + k * 1024); } while (0)
; #define PG8_LDB(dst, b, h) do { _Pragma("unroll") for (int n = 0; n < 2; ++n) _Pragma("unroll") for (int k = 0; k < 2; ++k) dst[n][k] = *(const LAS bf16x8*)(lds + PG8_SB(b, h) + boff + n * 2048 + k * 1024); } while (0)
; #define PG8_MMA(ai, bj, At, Bt) do { __builtin_amdgcn_s_setprio(1); _Pragma("unroll") for (int m = 0; m < 4; ++m) _Pragma("unroll") for (int n = 0; n < 2; ++n) _Pragma("unroll") for (int k = 0; k < 2; ++k) \
;         acc[ai][bj][m][n] = __builtin_amdgcn_mfma_f32_16x16x32_bf16(Bt[n][k], At[m][k], acc[ai][bj][m][n], 0, 0, 0); __builtin_amdgcn_s_setprio(0); } while (0)
; #define PG8_WAIT_V(n) asm volatile("s_waitcnt vmcnt(" #n ")" ::: "memory")
; #define PG8_WAIT_L(n) asm volatile("s_waitcnt lgkmcnt(" #n ")" ::: "memory")
; #define PG8_BAR __builtin_amdgcn_s_barrier()
; #define PG8_SCHED __builtin_amdgcn_sched_barrier(0)
; __device__ __forceinline__ void gemm_phase(LAS unsigned char* lds, const Call& C, const int tid, const Args& args) {
;     ...
;             PG8_LDB(B0, 1, 0); PG8_LDB(B1, 1, 1); PG8_SCHED; PG8_LDA(At, 1, 0); PG8_STAGE(PG8_SA(0, 1), a2 + hstepA, voffA);
;             PG8_WAIT_V(8); PG8_WAIT_L(0); PG8_BAR; PG8_MMA(0, 0, At, B0); PG8_MMA(0, 1, At, B1); PG8_BAR; PG8_SCHED;
.Lp7_ph3:
	s_add_i32 s24, 0, 0x18000
	v_add_u32_e32 v80, s24, v245
	s_add_i32 s42, 0, 0x1c000
	ds_read_b128 v[136:139], v80
	ds_read_b128 v[140:143], v80 offset:1024
	ds_read_b128 v[144:147], v80 offset:2048
	ds_read_b128 v[148:151], v80 offset:3072
	v_add_u32_e32 v80, s42, v245
	ds_read_b128 v[152:155], v80
	ds_read_b128 v[156:159], v80 offset:1024
	ds_read_b128 v[160:163], v80 offset:2048
	ds_read_b128 v[164:167], v80 offset:3072
	s_add_u32 s34, s38, s22
	v_mov_b32_e32 v80, v205
	s_mov_b32 m0, s73
	ds_read_b128 v[168:171], v246 offset:32768
	ds_read_b128 v[172:175], v246 offset:33792
	ds_read_b128 v[176:179], v246 offset:34816
	ds_read_b128 v[180:183], v246 offset:35840
	ds_read_b128 v[184:187], v246 offset:36864
	ds_read_b128 v[188:191], v246 offset:37888
	ds_read_b128 v[192:195], v246 offset:38912
	ds_read_b128 v[196:199], v246 offset:39936
	s_addc_u32 s35, s39, 0
	s_nop 0
	global_load_lds_dwordx4 v80, s[34:35]
	v_mov_b32_e32 v80, v243
	s_mov_b32 m0, s4
	s_nop 0
	global_load_lds_dwordx4 v80, s[34:35]
	s_nop 0
	s_waitcnt vmcnt(8)
	s_waitcnt lgkmcnt(0)
	s_barrier
	s_setprio 1
	s_waitcnt lgkmcnt(0)
	v_mfma_f32_16x16x32_bf16 v[132:135], v[136:139], v[168:171], v[132:135]
	v_mfma_f32_16x16x32_bf16 v[128:131], v[144:147], v[168:171], v[128:131]
	v_mfma_f32_16x16x32_bf16 v[124:127], v[136:139], v[176:179], v[124:127]
	v_mfma_f32_16x16x32_bf16 v[120:123], v[144:147], v[176:179], v[120:123]
	v_mfma_f32_16x16x32_bf16 v[108:111], v[136:139], v[184:187], v[108:111]
	v_mfma_f32_16x16x32_bf16 v[104:107], v[144:147], v[184:187], v[104:107]
	v_mfma_f32_16x16x32_bf16 v[90:93], v[136:139], v[192:195], v[92:95]
	v_mfma_f32_16x16x32_bf16 v[86:89], v[144:147], v[192:195], v[86:89]
	v_mfma_f32_16x16x32_bf16 v[132:135], v[140:143], v[172:175], v[132:135]
	v_mfma_f32_16x16x32_bf16 v[128:131], v[148:151], v[172:175], v[128:131]
	v_mfma_f32_16x16x32_bf16 v[124:127], v[140:143], v[180:183], v[124:127]
	v_mfma_f32_16x16x32_bf16 v[120:123], v[148:151], v[180:183], v[120:123]
	v_mfma_f32_16x16x32_bf16 v[108:111], v[140:143], v[188:191], v[108:111]
	v_mfma_f32_16x16x32_bf16 v[104:107], v[148:151], v[188:191], v[104:107]
	v_mfma_f32_16x16x32_bf16 v[92:95], v[140:143], v[196:199], v[90:93]
	v_mfma_f32_16x16x32_bf16 v[88:91], v[148:151], v[196:199], v[86:89]
	s_setprio 0
	s_setprio 1
	v_mfma_f32_16x16x32_bf16 v[116:119], v[152:155], v[168:171], v[116:119]
	v_mfma_f32_16x16x32_bf16 v[112:115], v[160:163], v[168:171], v[112:115]
	v_mfma_f32_16x16x32_bf16 v[100:103], v[152:155], v[176:179], v[100:103]
	v_mfma_f32_16x16x32_bf16 v[96:99], v[160:163], v[176:179], v[96:99]
	v_mfma_f32_16x16x32_bf16 v[76:79], v[152:155], v[184:187], v[76:79]
	v_mfma_f32_16x16x32_bf16 v[72:75], v[160:163], v[184:187], v[72:75]
	v_mfma_f32_16x16x32_bf16 v[68:71], v[152:155], v[192:195], v[68:71]
	v_mfma_f32_16x16x32_bf16 v[60:63], v[160:163], v[192:195], v[60:63]
	v_mfma_f32_16x16x32_bf16 v[116:119], v[156:159], v[172:175], v[116:119]
	v_mfma_f32_16x16x32_bf16 v[112:115], v[164:167], v[172:175], v[112:115]
	v_mfma_f32_16x16x32_bf16 v[100:103], v[156:159], v[180:183], v[100:103]
	v_mfma_f32_16x16x32_bf16 v[96:99], v[164:167], v[180:183], v[96:99]
	v_mfma_f32_16x16x32_bf16 v[76:79], v[156:159], v[188:191], v[76:79]
	v_mfma_f32_16x16x32_bf16 v[72:75], v[164:167], v[188:191], v[72:75]
	v_mfma_f32_16x16x32_bf16 v[68:71], v[156:159], v[196:199], v[68:71]
	v_mfma_f32_16x16x32_bf16 v[60:63], v[164:167], v[196:199], v[60:63]
	s_setprio 0
	s_barrier
; #define PG8_STAGE(bufoff, gbase, voff) do { _Pragma("unroll") for (int _i = 0; _i < 2; ++_i) { unsigned _vo = (voff)[_i]; asm volatile("" : "+v"(_vo));   \
;         __builtin_amdgcn_global_load_lds((const unsigned*)((const char*)(gbase) + _vo), (LAS unsigned*)(lds + (bufoff) + ldsw + _i * 8192), 16, 0, 0); } } while (0)
; #define PG8_LDA(dst, b, h) do { _Pragma("unroll") for (int m = 0; m < 4; ++m) _Pragma("unroll") for (int k = 0; k < 2; ++k) dst[m][k] = *(const LAS bf16x8*)(lds + PG8_SA(b, h) + aoff + m * 2048 + k * 1024); } while (0)
; #define PG8_MMA(ai, bj, At, Bt) do { __builtin_amdgcn_s_setprio(1); _Pragma("unroll") for (int m = 0; m < 4; ++m) _Pragma("unroll") for (int n = 0; n < 2; ++n) _Pragma("unroll") for (int k = 0; k < 2; ++k) \
;         acc[ai][bj][m][n] = __builtin_amdgcn_mfma_f32_16x16x32_bf16(Bt[n][k], At[m][k], acc[ai][bj][m][n], 0, 0, 0); __builtin_amdgcn_s_setprio(0); } while (0)
; #define PG8_WAIT_V(n) asm volatile("s_waitcnt vmcnt(" #n ")" ::: "memory")
; #define PG8_WAIT_L(n) asm volatile("s_waitcnt lgkmcnt(" #n ")" ::: "memory")
; #define PG8_BAR __builtin_amdgcn_s_barrier()
; #define PG8_SCHED __builtin_amdgcn_sched_barrier(0)
; __device__ __forceinline__ void gemm_phase(LAS unsigned char* lds, const Call& C, const int tid, const Args& args) {
;     ...
;             PG8_LDA(At, 1, 1); PG8_STAGE(PG8_SB(1, 0), b3, voffB); PG8_STAGE(PG8_SB(1, 1), b3 + hstepB, voffB); PG8_STAGE(PG8_SA(1, 0), a3, voffA);
;             PG8_WAIT_V(8); PG8_WAIT_L(0); PG8_BAR; PG8_MMA(1, 0, At, B0); PG8_MMA(1, 1, At, B1); PG8_BAR; PG8_SCHED;
;         }
	s_nop 0
	v_mov_b32_e32 v80, v242
	ds_read_b128 v[168:171], v246 offset:49152
	ds_read_b128 v[172:175], v246 offset:50176
	ds_read_b128 v[176:179], v246 offset:51200
	ds_read_b128 v[180:183], v246 offset:52224
	ds_read_b128 v[184:187], v246 offset:53248
	ds_read_b128 v[188:191], v246 offset:54272
	ds_read_b128 v[192:195], v246 offset:55296
	ds_read_b128 v[196:199], v246 offset:56320
	s_add_i32 s24, s24, s23
	v_lshl_add_u64 v[82:83], s[40:41], 0, v[80:81]
	v_lshl_add_u64 v[82:83], v[82:83], 0, s[18:19]
	s_mov_b32 m0, s24
	v_mov_b32_e32 v80, v244
	global_load_lds_dwordx4 v[82:83], off
	s_add_i32 m0, s24, 0x2000
	v_lshl_add_u64 v[82:83], s[40:41], 0, v[80:81]
	v_lshl_add_u64 v[82:83], v[82:83], 0, s[18:19]
	v_mov_b32_e32 v80, v242
	global_load_lds_dwordx4 v[82:83], off
	s_add_i32 s24, s42, s23
	v_lshl_add_u64 v[82:83], s[0:1], 0, v[80:81]
	v_lshl_add_u64 v[82:83], v[82:83], 0, s[18:19]
	s_mov_b32 m0, s24
	v_mov_b32_e32 v80, v244
	global_load_lds_dwordx4 v[82:83], off
	s_add_i32 m0, s24, 0x2000
	v_lshl_add_u64 v[82:83], s[0:1], 0, v[80:81]
	v_lshl_add_u64 v[82:83], v[82:83], 0, s[18:19]
	v_mov_b32_e32 v80, v205
	global_load_lds_dwordx4 v[82:83], off
	s_mov_b32 m0, s14
	v_lshl_add_u64 v[82:83], s[38:39], 0, v[80:81]
	v_lshl_add_u64 v[82:83], v[82:83], 0, s[18:19]
	v_mov_b32_e32 v80, v243
	global_load_lds_dwordx4 v[82:83], off
	s_mov_b32 m0, s52
	v_lshl_add_u64 v[82:83], s[38:39], 0, v[80:81]
	v_lshl_add_u64 v[82:83], v[82:83], 0, s[18:19]
	global_load_lds_dwordx4 v[82:83], off
	s_waitcnt vmcnt(8)
	s_waitcnt lgkmcnt(0)
	s_barrier
	s_setprio 1
	s_waitcnt lgkmcnt(0)
	v_mfma_f32_16x16x32_bf16 v[64:67], v[136:139], v[168:171], v[64:67]
	v_mfma_f32_16x16x32_bf16 v[56:59], v[144:147], v[168:171], v[56:59]
	v_mfma_f32_16x16x32_bf16 v[52:55], v[136:139], v[176:179], v[52:55]
	v_mfma_f32_16x16x32_bf16 v[48:51], v[144:147], v[176:179], v[48:51]
	v_mfma_f32_16x16x32_bf16 v[36:39], v[136:139], v[184:187], v[36:39]
	v_mfma_f32_16x16x32_bf16 v[32:35], v[144:147], v[184:187], v[32:35]
	v_mfma_f32_16x16x32_bf16 v[20:23], v[136:139], v[192:195], v[20:23]
	v_mfma_f32_16x16x32_bf16 v[16:19], v[144:147], v[192:195], v[16:19]
	v_mfma_f32_16x16x32_bf16 v[64:67], v[140:143], v[172:175], v[64:67]
	v_mfma_f32_16x16x32_bf16 v[56:59], v[148:151], v[172:175], v[56:59]
	v_mfma_f32_16x16x32_bf16 v[52:55], v[140:143], v[180:183], v[52:55]
	v_mfma_f32_16x16x32_bf16 v[48:51], v[148:151], v[180:183], v[48:51]
	v_mfma_f32_16x16x32_bf16 v[36:39], v[140:143], v[188:191], v[36:39]
	v_mfma_f32_16x16x32_bf16 v[32:35], v[148:151], v[188:191], v[32:35]
	v_mfma_f32_16x16x32_bf16 v[20:23], v[140:143], v[196:199], v[20:23]
	v_mfma_f32_16x16x32_bf16 v[16:19], v[148:151], v[196:199], v[16:19]
	s_setprio 0
	s_setprio 1
	v_mfma_f32_16x16x32_bf16 v[44:47], v[152:155], v[168:171], v[44:47]
	v_mfma_f32_16x16x32_bf16 v[40:43], v[160:163], v[168:171], v[40:43]
	v_mfma_f32_16x16x32_bf16 v[28:31], v[152:155], v[176:179], v[28:31]
	v_mfma_f32_16x16x32_bf16 v[24:27], v[160:163], v[176:179], v[24:27]
	v_mfma_f32_16x16x32_bf16 v[12:15], v[152:155], v[184:187], v[12:15]
	v_mfma_f32_16x16x32_bf16 v[8:11], v[160:163], v[184:187], v[8:11]
	v_mfma_f32_16x16x32_bf16 v[4:7], v[152:155], v[192:195], v[4:7]
	v_mfma_f32_16x16x32_bf16 v[0:3], v[160:163], v[192:195], v[0:3]
	v_mfma_f32_16x16x32_bf16 v[44:47], v[156:159], v[172:175], v[44:47]
	v_mfma_f32_16x16x32_bf16 v[40:43], v[164:167], v[172:175], v[40:43]
	v_mfma_f32_16x16x32_bf16 v[28:31], v[156:159], v[180:183], v[28:31]
	v_mfma_f32_16x16x32_bf16 v[24:27], v[164:167], v[180:183], v[24:27]
	v_mfma_f32_16x16x32_bf16 v[12:15], v[156:159], v[188:191], v[12:15]
	v_mfma_f32_16x16x32_bf16 v[8:11], v[164:167], v[188:191], v[8:11]
	v_mfma_f32_16x16x32_bf16 v[4:7], v[156:159], v[196:199], v[4:7]
	v_mfma_f32_16x16x32_bf16 v[0:3], v[164:167], v[196:199], v[0:3]
	s_setprio 0
	s_barrier
	s_add_u32 s16, s16, 0x100
	s_addc_u32 s17, s17, 0
	s_cmp_ge_u32 s25, s12
	s_mov_b64 s[0:1], s[8:9]
	s_mov_b32 s24, s25
	s_cbranch_scc0 .LBB0_282
	s_and_b64 vcc, exec, s[80:81]
	s_cbranch_vccz .LBB0_285
